# grid barrier: waiting workgroups poll the cross-XCD release generation directly instead of the per-XCD relay word (one hop less on the release path)
# speedup vs baseline: 1.0082x; 1.0026x over previous
.LBB0_46:
	s_or_b64 exec, exec, s[38:39]
	v_cvt_f32_u32_e32 v4, v2
	s_waitcnt vmcnt(0)
	v_readfirstlane_b32 s6, v3
	v_sub_u32_e32 v3, 0, v2
	v_rcp_iflag_f32_e32 v4, v4
	v_add_u32_e32 v5, s6, v1
	v_mul_f32_e32 v4, 0x4f7ffffe, v4
	v_cvt_u32_f32_e32 v4, v4
	v_mul_lo_u32 v1, v3, v4
	v_mul_hi_u32 v1, v4, v1
	v_add_u32_e32 v1, v4, v1
	v_mul_hi_u32 v1, v5, v1
	v_mul_lo_u32 v3, v1, v2
	v_sub_u32_e32 v3, v5, v3
	v_add_u32_e32 v4, 1, v1
	v_sub_u32_e32 v6, v3, v2
	v_cmp_ge_u32_e32 vcc, v3, v2
	s_nop 1
	v_cndmask_b32_e32 v1, v1, v4, vcc
	v_cndmask_b32_e32 v3, v3, v6, vcc
	v_add_u32_e32 v4, 1, v1
	v_cmp_ge_u32_e32 vcc, v3, v2
	v_add_u32_e32 v3, 1, v5
	s_nop 0
	v_cndmask_b32_e32 v1, v1, v4, vcc
	v_mul_lo_u32 v4, v2, v1
	v_add_u32_e32 v2, v4, v2
	v_cmp_ne_u32_e32 vcc, v3, v2
	s_and_saveexec_b64 s[6:7], vcc
	s_xor_b64 s[38:39], exec, s[6:7]
	s_cbranch_execz .LBB0_60
	v_readlane_b32 s6, v246, 46
	s_waitcnt lgkmcnt(0)
	v_mov_b32_e32 v0, 0
	v_readlane_b32 s7, v246, 47
	s_nop 4
	global_load_dword v2, v0, s[6:7] sc1
	s_waitcnt vmcnt(0)
	v_cmp_eq_u32_e32 vcc, v2, v1
	s_and_saveexec_b64 s[40:41], vcc
	s_cbranch_execz .LBB0_59
	s_mov_b32 s6, 1
	s_mov_b64 s[44:45], 0
	s_branch .LBB0_50

.LBB0_52:
	v_readlane_b32 s16, v246, 46
	v_readlane_b32 s17, v246, 47
	s_add_i32 s6, s6, 1
	s_mov_b64 s[50:51], -1
	s_nop 2
	global_load_dword v2, v0, s[16:17] sc1
	s_waitcnt vmcnt(0)
	v_cmp_ne_u32_e32 vcc, v2, v1
	s_orn2_b64 s[48:49], vcc, exec
	s_branch .LBB0_49

.LBB0_314:
	s_or_b64 exec, exec, s[8:9]
	v_cvt_f32_u32_e32 v4, v2
	s_waitcnt vmcnt(0)
	v_readfirstlane_b32 s6, v3
	v_sub_u32_e32 v3, 0, v2
	v_rcp_iflag_f32_e32 v4, v4
	v_add_u32_e32 v5, s6, v1
	v_mul_f32_e32 v4, 0x4f7ffffe, v4
	v_cvt_u32_f32_e32 v4, v4
	v_mul_lo_u32 v1, v3, v4
	v_mul_hi_u32 v1, v4, v1
	v_add_u32_e32 v1, v4, v1
	v_mul_hi_u32 v1, v5, v1
	v_mul_lo_u32 v3, v1, v2
	v_sub_u32_e32 v3, v5, v3
	v_add_u32_e32 v4, 1, v1
	v_sub_u32_e32 v6, v3, v2
	v_cmp_ge_u32_e32 vcc, v3, v2
	s_nop 1
	v_cndmask_b32_e32 v1, v1, v4, vcc
	v_cndmask_b32_e32 v3, v3, v6, vcc
	v_add_u32_e32 v4, 1, v1
	v_cmp_ge_u32_e32 vcc, v3, v2
	v_add_u32_e32 v3, 1, v5
	s_nop 0
	v_cndmask_b32_e32 v1, v1, v4, vcc
	v_mul_lo_u32 v4, v2, v1
	v_add_u32_e32 v2, v4, v2
	v_cmp_ne_u32_e32 vcc, v3, v2
	s_and_saveexec_b64 s[6:7], vcc
	s_xor_b64 s[8:9], exec, s[6:7]
	s_cbranch_execz .LBB0_328
	v_readlane_b32 s6, v246, 46
	s_waitcnt lgkmcnt(0)
	v_mov_b32_e32 v0, 0
	v_readlane_b32 s7, v246, 47
	s_nop 4
	global_load_dword v2, v0, s[6:7] sc1
	s_waitcnt vmcnt(0)
	v_cmp_eq_u32_e32 vcc, v2, v1
	s_and_saveexec_b64 s[38:39], vcc
	s_cbranch_execz .LBB0_327
	s_mov_b32 s6, 1
	s_mov_b64 s[40:41], 0
	s_branch .LBB0_318

.LBB0_320:
	v_readlane_b32 s30, v246, 46
	v_readlane_b32 s31, v246, 47
	s_add_i32 s6, s6, 1
	s_mov_b64 s[48:49], -1
	s_nop 2
	global_load_dword v2, v0, s[30:31] sc1
	s_waitcnt vmcnt(0)
	v_cmp_ne_u32_e32 vcc, v2, v1
	s_orn2_b64 s[46:47], vcc, exec
	s_branch .LBB0_317

.LBB0_464:
	s_or_b64 exec, exec, s[8:9]
	v_cvt_f32_u32_e32 v4, v2
	s_waitcnt vmcnt(0)
	v_readfirstlane_b32 s6, v3
	v_sub_u32_e32 v3, 0, v2
	v_rcp_iflag_f32_e32 v4, v4
	v_add_u32_e32 v5, s6, v1
	v_mul_f32_e32 v4, 0x4f7ffffe, v4
	v_cvt_u32_f32_e32 v4, v4
	v_mul_lo_u32 v1, v3, v4
	v_mul_hi_u32 v1, v4, v1
	v_add_u32_e32 v1, v4, v1
	v_mul_hi_u32 v1, v5, v1
	v_mul_lo_u32 v3, v1, v2
	v_sub_u32_e32 v3, v5, v3
	v_add_u32_e32 v4, 1, v1
	v_cmp_ge_u32_e32 vcc, v3, v2
	s_nop 1
	v_cndmask_b32_e32 v1, v1, v4, vcc
	v_sub_u32_e32 v4, v3, v2
	v_cndmask_b32_e32 v3, v3, v4, vcc
	v_add_u32_e32 v4, 1, v1
	v_cmp_ge_u32_e32 vcc, v3, v2
	v_add_u32_e32 v3, 1, v5
	s_nop 0
	v_cndmask_b32_e32 v1, v1, v4, vcc
	v_mul_lo_u32 v4, v2, v1
	v_add_u32_e32 v2, v4, v2
	v_cmp_ne_u32_e32 vcc, v3, v2
	s_and_saveexec_b64 s[6:7], vcc
	s_xor_b64 s[8:9], exec, s[6:7]
	s_cbranch_execz .LBB0_478
	s_waitcnt lgkmcnt(0)
	v_mov_b32_e32 v0, 0
	global_load_dword v2, v0, s[84:85] sc1
	s_waitcnt vmcnt(0)
	v_cmp_eq_u32_e32 vcc, v2, v1
	s_and_saveexec_b64 s[12:13], vcc
	s_cbranch_execz .LBB0_477
	s_mov_b32 s6, 1
	s_mov_b64 s[14:15], 0
	s_branch .LBB0_468

.LBB0_470:
	global_load_dword v2, v0, s[84:85] sc1
	s_add_i32 s6, s6, 1
	s_mov_b64 s[40:41], -1
	s_waitcnt vmcnt(0)
	v_cmp_ne_u32_e32 vcc, v2, v1
	s_orn2_b64 s[38:39], vcc, exec
	s_branch .LBB0_467

.LBB0_530:
	s_or_b64 exec, exec, s[12:13]
	v_cvt_f32_u32_e32 v4, v2
	s_waitcnt vmcnt(0)
	v_readfirstlane_b32 s6, v3
	v_sub_u32_e32 v3, 0, v2
	v_rcp_iflag_f32_e32 v4, v4
	v_add_u32_e32 v5, s6, v1
	v_mul_f32_e32 v4, 0x4f7ffffe, v4
	v_cvt_u32_f32_e32 v4, v4
	v_mul_lo_u32 v1, v3, v4
	v_mul_hi_u32 v1, v4, v1
	v_add_u32_e32 v1, v4, v1
	v_mul_hi_u32 v1, v5, v1
	v_mul_lo_u32 v3, v1, v2
	v_sub_u32_e32 v3, v5, v3
	v_add_u32_e32 v4, 1, v1
	v_cmp_ge_u32_e32 vcc, v3, v2
	s_nop 1
	v_cndmask_b32_e32 v1, v1, v4, vcc
	v_sub_u32_e32 v4, v3, v2
	v_cndmask_b32_e32 v3, v3, v4, vcc
	v_add_u32_e32 v4, 1, v1
	v_cmp_ge_u32_e32 vcc, v3, v2
	v_add_u32_e32 v3, 1, v5
	s_nop 0
	v_cndmask_b32_e32 v1, v1, v4, vcc
	v_mul_lo_u32 v4, v2, v1
	v_add_u32_e32 v2, v4, v2
	v_cmp_ne_u32_e32 vcc, v3, v2
	s_and_saveexec_b64 s[6:7], vcc
	s_xor_b64 s[12:13], exec, s[6:7]
	s_cbranch_execz .LBB0_544
	s_waitcnt lgkmcnt(0)
	v_mov_b32_e32 v0, 0
	global_load_dword v2, v0, s[84:85] sc1
	s_waitcnt vmcnt(0)
	v_cmp_eq_u32_e32 vcc, v2, v1
	s_and_saveexec_b64 s[14:15], vcc
	s_cbranch_execz .LBB0_543
	s_mov_b32 s6, 1
	s_mov_b64 s[18:19], 0
	s_branch .LBB0_534

.LBB0_536:
	global_load_dword v2, v0, s[84:85] sc1
	s_add_i32 s6, s6, 1
	s_mov_b64 s[42:43], -1
	s_waitcnt vmcnt(0)
	v_cmp_ne_u32_e32 vcc, v2, v1
	s_orn2_b64 s[40:41], vcc, exec
	s_branch .LBB0_533

.LBB0_621:
	s_or_b64 exec, exec, s[4:5]
	v_cvt_f32_u32_e32 v4, v2
	s_waitcnt vmcnt(0)
	v_readfirstlane_b32 s4, v3
	v_sub_u32_e32 v3, 0, v2
	v_rcp_iflag_f32_e32 v4, v4
	v_add_u32_e32 v5, s4, v1
	v_mul_f32_e32 v4, 0x4f7ffffe, v4
	v_cvt_u32_f32_e32 v4, v4
	v_mul_lo_u32 v1, v3, v4
	v_mul_hi_u32 v1, v4, v1
	v_add_u32_e32 v1, v4, v1
	v_mul_hi_u32 v1, v5, v1
	v_mul_lo_u32 v3, v1, v2
	v_sub_u32_e32 v3, v5, v3
	v_add_u32_e32 v4, 1, v1
	v_cmp_ge_u32_e32 vcc, v3, v2
	s_nop 1
	v_cndmask_b32_e32 v1, v1, v4, vcc
	v_sub_u32_e32 v4, v3, v2
	v_cndmask_b32_e32 v3, v3, v4, vcc
	v_add_u32_e32 v4, 1, v1
	v_cmp_ge_u32_e32 vcc, v3, v2
	v_add_u32_e32 v3, 1, v5
	s_nop 0
	v_cndmask_b32_e32 v1, v1, v4, vcc
	v_mul_lo_u32 v4, v2, v1
	v_add_u32_e32 v2, v4, v2
	v_cmp_ne_u32_e32 vcc, v3, v2
	s_and_saveexec_b64 s[4:5], vcc
	s_xor_b64 s[4:5], exec, s[4:5]
	s_cbranch_execz .LBB0_635
	s_waitcnt lgkmcnt(0)
	v_mov_b32_e32 v0, 0
	global_load_dword v2, v0, s[84:85] sc1
	s_waitcnt vmcnt(0)
	v_cmp_eq_u32_e32 vcc, v2, v1
	s_and_saveexec_b64 s[10:11], vcc
	s_cbranch_execz .LBB0_634
	s_mov_b32 s6, 1
	s_mov_b64 s[14:15], 0
	s_branch .LBB0_625

.LBB0_789:
	s_or_b64 exec, exec, s[10:11]
	v_cvt_f32_u32_e32 v4, v2
	s_waitcnt vmcnt(0)
	v_readfirstlane_b32 s6, v3
	v_sub_u32_e32 v3, 0, v2
	v_rcp_iflag_f32_e32 v4, v4
	v_add_u32_e32 v5, s6, v1
	v_mul_f32_e32 v4, 0x4f7ffffe, v4
	v_cvt_u32_f32_e32 v4, v4
	v_mul_lo_u32 v1, v3, v4
	v_mul_hi_u32 v1, v4, v1
	v_add_u32_e32 v1, v4, v1
	v_mul_hi_u32 v1, v5, v1
	v_mul_lo_u32 v3, v1, v2
	v_sub_u32_e32 v3, v5, v3
	v_add_u32_e32 v4, 1, v1
	v_cmp_ge_u32_e32 vcc, v3, v2
	s_nop 1
	v_cndmask_b32_e32 v1, v1, v4, vcc
	v_sub_u32_e32 v4, v3, v2
	v_cndmask_b32_e32 v3, v3, v4, vcc
	v_add_u32_e32 v4, 1, v1
	v_cmp_ge_u32_e32 vcc, v3, v2
	v_add_u32_e32 v3, 1, v5
	s_nop 0
	v_cndmask_b32_e32 v1, v1, v4, vcc
	v_mul_lo_u32 v4, v2, v1
	v_add_u32_e32 v2, v4, v2
	v_cmp_ne_u32_e32 vcc, v3, v2
	s_and_saveexec_b64 s[6:7], vcc
	s_xor_b64 s[10:11], exec, s[6:7]
	s_cbranch_execz .LBB0_803
	s_waitcnt lgkmcnt(0)
	v_mov_b32_e32 v0, 0
	global_load_dword v2, v0, s[84:85] sc1
	s_waitcnt vmcnt(0)
	v_cmp_eq_u32_e32 vcc, v2, v1
	s_and_saveexec_b64 s[12:13], vcc
	s_cbranch_execz .LBB0_802
	s_mov_b32 s6, 1
	s_mov_b64 s[14:15], 0
	s_branch .LBB0_793

.LBB0_942:
	s_or_b64 exec, exec, s[10:11]
	v_cvt_f32_u32_e32 v4, v2
	s_waitcnt vmcnt(0)
	v_readfirstlane_b32 s10, v3
	v_sub_u32_e32 v3, 0, v2
	v_rcp_iflag_f32_e32 v4, v4
	v_add_u32_e32 v5, s10, v1
	v_mul_f32_e32 v4, 0x4f7ffffe, v4
	v_cvt_u32_f32_e32 v4, v4
	v_mul_lo_u32 v1, v3, v4
	v_mul_hi_u32 v1, v4, v1
	v_add_u32_e32 v1, v4, v1
	v_mul_hi_u32 v1, v5, v1
	v_mul_lo_u32 v3, v1, v2
	v_sub_u32_e32 v3, v5, v3
	v_add_u32_e32 v4, 1, v1
	v_cmp_ge_u32_e32 vcc, v3, v2
	s_nop 1
	v_cndmask_b32_e32 v1, v1, v4, vcc
	v_sub_u32_e32 v4, v3, v2
	v_cndmask_b32_e32 v3, v3, v4, vcc
	v_add_u32_e32 v4, 1, v1
	v_cmp_ge_u32_e32 vcc, v3, v2
	v_add_u32_e32 v3, 1, v5
	s_nop 0
	v_cndmask_b32_e32 v1, v1, v4, vcc
	v_mul_lo_u32 v4, v2, v1
	v_add_u32_e32 v2, v4, v2
	v_cmp_ne_u32_e32 vcc, v3, v2
	s_and_saveexec_b64 s[10:11], vcc
	s_xor_b64 s[10:11], exec, s[10:11]
	s_cbranch_execz .LBB0_956
	s_waitcnt lgkmcnt(0)
	v_mov_b32_e32 v0, 0
	global_load_dword v2, v0, s[84:85] sc1
	s_waitcnt vmcnt(0)
	v_cmp_eq_u32_e32 vcc, v2, v1
	s_and_saveexec_b64 s[12:13], vcc
	s_cbranch_execz .LBB0_955
	s_mov_b32 s17, 1
	s_mov_b64 s[14:15], 0
	s_branch .LBB0_946

.LBB0_948:
	global_load_dword v2, v0, s[84:85] sc1
	s_add_i32 s17, s17, 1
	s_mov_b64 s[42:43], -1
	s_waitcnt vmcnt(0)
	v_cmp_ne_u32_e32 vcc, v2, v1
	s_orn2_b64 s[40:41], vcc, exec
	s_branch .LBB0_945

.LBB0_1014:
	s_or_b64 exec, exec, s[10:11]
	v_cvt_f32_u32_e32 v4, v2
	s_waitcnt vmcnt(0)
	v_readfirstlane_b32 s3, v3
	v_sub_u32_e32 v3, 0, v2
	v_rcp_iflag_f32_e32 v4, v4
	v_add_u32_e32 v5, s3, v1
	v_mul_f32_e32 v4, 0x4f7ffffe, v4
	v_cvt_u32_f32_e32 v4, v4
	v_mul_lo_u32 v1, v3, v4
	v_mul_hi_u32 v1, v4, v1
	v_add_u32_e32 v1, v4, v1
	v_mul_hi_u32 v1, v5, v1
	v_mul_lo_u32 v3, v1, v2
	v_sub_u32_e32 v3, v5, v3
	v_add_u32_e32 v4, 1, v1
	v_cmp_ge_u32_e32 vcc, v3, v2
	s_nop 1
	v_cndmask_b32_e32 v1, v1, v4, vcc
	v_sub_u32_e32 v4, v3, v2
	v_cndmask_b32_e32 v3, v3, v4, vcc
	v_add_u32_e32 v4, 1, v1
	v_cmp_ge_u32_e32 vcc, v3, v2
	v_add_u32_e32 v3, 1, v5
	s_nop 0
	v_cndmask_b32_e32 v1, v1, v4, vcc
	v_mul_lo_u32 v4, v2, v1
	v_add_u32_e32 v2, v4, v2
	v_cmp_ne_u32_e32 vcc, v3, v2
	s_and_saveexec_b64 s[10:11], vcc
	s_xor_b64 s[10:11], exec, s[10:11]
	s_cbranch_execz .LBB0_1028
	s_waitcnt lgkmcnt(0)
	v_mov_b32_e32 v0, 0
	global_load_dword v2, v0, s[84:85] sc1
	s_waitcnt vmcnt(0)
	v_cmp_eq_u32_e32 vcc, v2, v1
	s_and_saveexec_b64 s[18:19], vcc
	s_cbranch_execz .LBB0_1027
	s_mov_b32 s3, 1
	s_mov_b64 s[38:39], 0
	s_branch .LBB0_1018

.LBB0_1020:
	global_load_dword v2, v0, s[84:85] sc1
	s_add_i32 s3, s3, 1
	s_mov_b64 s[44:45], -1
	s_waitcnt vmcnt(0)
	v_cmp_ne_u32_e32 vcc, v2, v1
	s_orn2_b64 s[42:43], vcc, exec
	s_branch .LBB0_1017

.LBB0_1132:
	s_or_b64 exec, exec, s[8:9]
	v_cvt_f32_u32_e32 v4, v2
	s_waitcnt vmcnt(0)
	v_readfirstlane_b32 s3, v3
	v_sub_u32_e32 v3, 0, v2
	v_rcp_iflag_f32_e32 v4, v4
	v_add_u32_e32 v5, s3, v1
	v_mul_f32_e32 v4, 0x4f7ffffe, v4
	v_cvt_u32_f32_e32 v4, v4
	v_mul_lo_u32 v1, v3, v4
	v_mul_hi_u32 v1, v4, v1
	v_add_u32_e32 v1, v4, v1
	v_mul_hi_u32 v1, v5, v1
	v_mul_lo_u32 v3, v1, v2
	v_sub_u32_e32 v3, v5, v3
	v_add_u32_e32 v4, 1, v1
	v_cmp_ge_u32_e32 vcc, v3, v2
	s_nop 1
	v_cndmask_b32_e32 v1, v1, v4, vcc
	v_sub_u32_e32 v4, v3, v2
	v_cndmask_b32_e32 v3, v3, v4, vcc
	v_add_u32_e32 v4, 1, v1
	v_cmp_ge_u32_e32 vcc, v3, v2
	v_add_u32_e32 v3, 1, v5
	s_nop 0
	v_cndmask_b32_e32 v1, v1, v4, vcc
	v_mul_lo_u32 v4, v2, v1
	v_add_u32_e32 v2, v4, v2
	v_cmp_ne_u32_e32 vcc, v3, v2
	s_and_saveexec_b64 s[6:7], vcc
	s_xor_b64 s[8:9], exec, s[6:7]
	s_cbranch_execz .LBB0_1146
	s_waitcnt lgkmcnt(0)
	v_mov_b32_e32 v0, 0
	global_load_dword v2, v0, s[84:85] sc1
	s_waitcnt vmcnt(0)
	v_cmp_eq_u32_e32 vcc, v2, v1
	s_and_saveexec_b64 s[12:13], vcc
	s_cbranch_execz .LBB0_1145
	s_mov_b32 s3, 1
	s_mov_b64 s[14:15], 0
	s_branch .LBB0_1136

.LBB0_1138:
	global_load_dword v2, v0, s[84:85] sc1
	s_add_i32 s3, s3, 1
	s_mov_b64 s[34:35], -1
	s_waitcnt vmcnt(0)
	v_cmp_ne_u32_e32 vcc, v2, v1
	s_orn2_b64 s[30:31], vcc, exec
	s_branch .LBB0_1135
